# Fourier stage-A tile epilogue: the 8 twiddle loads issued together with counted vmcnt waits instead of a vmcnt(0) drain per row
# baseline (speedup 1.0000x reference)
; #define LAS __attribute__((address_space(3)))
; #define MFMA32(a, b, c) __builtin_amdgcn_mfma_f32_32x32x16_bf16((a), (b), (c), 0, 0, 0)
; __device__ __forceinline__ unsigned pk2(float lo, float hi) { return cvt_pk_bf16(lo, hi); }
; #define lane (pg8::pg8_lane_id())
; template <int MR, int KK, class Epi>
; __device__ __forceinline__ void dft_tiles(lds8* lds, const bf16_t* A, int wave, int lane, const Epi& epi) {
;     ...
;     for (int t = wave; t < (MR / 32) * 4; t += 8) { const int rb = t >> 2, nb = t & 3; f32x16 acc;
; #pragma unroll
;         for (int r = 0; r < 16; ++r) acc[r] = 0.f;
;         const int n = 32 * nb + l31, sw = (n & 15) ^ ((n >> 4) & 7);
;         const bf16_t* ap = A + (size_t)(32 * rb + l31) * KK + 8 * hh; const lds8* bp = lds + n * BS;
; #pragma unroll
;         for (int ks = 0; ks < KK / 16; ++ks) { const bf16x8 av = *(const bf16x8*)(ap + 16 * ks); const bf16x8 bv = *(const LAS bf16x8*)(bp + (((2 * ks + hh) ^ sw) << 4)); acc = MFMA32(av, bv, acc); }
;         epi(rb, nb, acc); }
; template <int S1>
; __device__ __forceinline__ void fourier_a_unit(lds8* lds, const bf16_t* H, bf16_t* TB, const bf16_t* G1, const float* tw, int seqb, int s2, int g, int tid, int lane, int wave) {
;     ...
;     auto epi = [&](int rb, int nb, const f32x16& acc) {
; #pragma unroll
;         for (int r = 0; r < 8; ++r) { const int k1 = 16 * rb + (r & 3) + 8 * (r >> 2) + 4 * hh; const f32x2v cs = *(const f32x2v*)(tw + 2 * (s2 * k1));
;             const float c = cs.x, s = cs.y; const float tr = acc[r], ti = acc[r + 8];
;             bf16_t* o = TB + ((size_t)seqb + (size_t)k1 * S1 + s2) * DM + g * 128 + 32 * nb + l31;
;             const unsigned w = pk2((tr * c + ti * s) * sc, (ti * c - tr * s) * sc); o[0] = (bf16_t)(w & 0xffffu); o[1024] = (bf16_t)(w >> 16); } };
;     dft_tiles<2 * S1, 2 * S1>(lds, G1, wave, lane, epi);
.LBB0_1203:
	v_lshl_add_u64 v[0:1], s[26:27], 0, v[48:49]
	v_add_u32_e32 v2, s63, v187
	v_add_co_u32_e32 v214, vcc, 0xbc60000, v0
	v_ashrrev_i32_e32 v3, 31, v2
	s_nop 0
	v_addc_co_u32_e32 v215, vcc, 0, v1, vcc
	v_lshl_add_u64 v[216:217], v[2:3], 2, s[28:29]
	global_load_dwordx4 v[0:3], v[214:215], off
	global_load_dwordx4 v[190:193], v[214:215], off offset:32
	global_load_dwordx4 v[194:197], v[214:215], off offset:64
	global_load_dwordx4 v[198:201], v[214:215], off offset:96
	s_and_b32 s8, s69, 0x60
	v_or_b32_e32 v4, s8, v55
	v_lshrrev_b32_e32 v5, 4, v4
	v_xor_b32_e32 v218, v5, v56
	v_lshl_add_u32 v189, v4, 8, 0
	v_xor_b32_e32 v4, v218, v54
	v_xor_b32_e32 v5, v218, v57
	v_lshl_add_u32 v4, v4, 4, v189
	v_lshl_add_u32 v8, v5, 4, v189
	ds_read_b128 v[4:7], v4
	ds_read_b128 v[202:205], v8
	global_load_dwordx4 v[206:209], v[214:215], off offset:128
	global_load_dwordx4 v[210:213], v[214:215], off offset:160
	v_xor_b32_e32 v219, v218, v58
	v_xor_b32_e32 v220, v218, v59
	v_lshl_add_u64 v[48:49], v[48:49], 0, s[54:55]
	s_addk_i32 s69, 0x100
	s_waitcnt vmcnt(5) lgkmcnt(1)
	v_mfma_f32_32x32x16_bf16 v[0:15], v[0:3], v[4:7], 0
	s_waitcnt vmcnt(4) lgkmcnt(0)
	v_mfma_f32_32x32x16_bf16 v[0:15], v[190:193], v[202:205], v[0:15]
	v_lshl_add_u32 v190, v219, 4, v189
	v_lshl_add_u32 v202, v220, 4, v189
	ds_read_b128 v[190:193], v190
	ds_read_b128 v[202:205], v202
	s_waitcnt vmcnt(3) lgkmcnt(1)
	v_mfma_f32_32x32x16_bf16 v[0:15], v[194:197], v[190:193], v[0:15]
	global_load_dwordx4 v[190:193], v[214:215], off offset:192
	global_load_dwordx4 v[194:197], v[214:215], off offset:224
	v_xor_b32_e32 v214, v218, v60
	v_xor_b32_e32 v215, v218, v61
	s_waitcnt vmcnt(4) lgkmcnt(0)
	v_mfma_f32_32x32x16_bf16 v[0:15], v[198:201], v[202:205], v[0:15]
	v_lshl_add_u32 v198, v214, 4, v189
	v_lshl_add_u32 v202, v215, 4, v189
	ds_read_b128 v[198:201], v198
	ds_read_b128 v[202:205], v202
	s_waitcnt vmcnt(3) lgkmcnt(1)
	v_mfma_f32_32x32x16_bf16 v[0:15], v[206:209], v[198:201], v[0:15]
	global_load_dwordx2 v[206:207], v[216:217], off
	v_add_u32_e32 v224, s63, v186
	v_ashrrev_i32_e32 v225, 31, v224
	v_lshl_add_u64 v[224:225], v[224:225], 2, s[28:29]
	global_load_dwordx2 v[224:225], v[224:225], off
	v_add_u32_e32 v226, s63, v185
	v_ashrrev_i32_e32 v227, 31, v226
	v_lshl_add_u64 v[226:227], v[226:227], 2, s[28:29]
	global_load_dwordx2 v[226:227], v[226:227], off
	v_add_u32_e32 v228, s63, v184
	v_ashrrev_i32_e32 v229, 31, v228
	v_lshl_add_u64 v[228:229], v[228:229], 2, s[28:29]
	global_load_dwordx2 v[228:229], v[228:229], off
	v_add_u32_e32 v230, s63, v183
	v_ashrrev_i32_e32 v231, 31, v230
	v_lshl_add_u64 v[230:231], v[230:231], 2, s[28:29]
	global_load_dwordx2 v[230:231], v[230:231], off
	v_add_u32_e32 v232, s63, v182
	v_ashrrev_i32_e32 v233, 31, v232
	v_lshl_add_u64 v[232:233], v[232:233], 2, s[28:29]
	global_load_dwordx2 v[232:233], v[232:233], off
	v_add_u32_e32 v234, s63, v181
	v_ashrrev_i32_e32 v235, 31, v234
	v_lshl_add_u64 v[234:235], v[234:235], 2, s[28:29]
	global_load_dwordx2 v[234:235], v[234:235], off
	v_add_u32_e32 v236, s63, v180
	v_ashrrev_i32_e32 v237, 31, v236
	v_lshl_add_u64 v[236:237], v[236:237], 2, s[28:29]
	global_load_dwordx2 v[236:237], v[236:237], off
	v_xor_b32_e32 v198, v218, v62
	v_xor_b32_e32 v199, v218, v63
	v_lshl_add_u32 v198, v198, 4, v189
	v_lshl_add_u32 v189, v199, 4, v189
	v_lshl_add_u64 v[208:209], s[26:27], 0, v[46:47]
	v_lshl_add_u64 v[46:47], v[46:47], 0, s[56:57]
	s_waitcnt vmcnt(10) lgkmcnt(0)
	v_mfma_f32_32x32x16_bf16 v[0:15], v[210:213], v[202:205], v[0:15]
	ds_read_b128 v[198:201], v198
	ds_read_b128 v[202:205], v189
	s_waitcnt vmcnt(9) lgkmcnt(1)
	v_mfma_f32_32x32x16_bf16 v[0:15], v[190:193], v[198:201], v[0:15]
	v_add_co_u32_e32 v192, vcc, s44, v208
	s_nop 1
	v_addc_co_u32_e32 v193, vcc, 0, v209, vcc
	s_waitcnt vmcnt(8) lgkmcnt(0)
; __device__ __forceinline__ unsigned pk2(float lo, float hi) { return cvt_pk_bf16(lo, hi); }
; #define lane (pg8::pg8_lane_id())
; template <int S1>
; __device__ __forceinline__ void fourier_a_unit(lds8* lds, const bf16_t* H, bf16_t* TB, const bf16_t* G1, const float* tw, int seqb, int s2, int g, int tid, int lane, int wave) {
;     ...
;     auto epi = [&](int rb, int nb, const f32x16& acc) {
; #pragma unroll
;         for (int r = 0; r < 8; ++r) { const int k1 = 16 * rb + (r & 3) + 8 * (r >> 2) + 4 * hh; const f32x2v cs = *(const f32x2v*)(tw + 2 * (s2 * k1));
;             const float c = cs.x, s = cs.y; const float tr = acc[r], ti = acc[r + 8];
;             bf16_t* o = TB + ((size_t)seqb + (size_t)k1 * S1 + s2) * DM + g * 128 + 32 * nb + l31;
;             const unsigned w = pk2((tr * c + ti * s) * sc, (ti * c - tr * s) * sc); o[0] = (bf16_t)(w & 0xffffu); o[1024] = (bf16_t)(w >> 16); } };
;     dft_tiles<2 * S1, 2 * S1>(lds, G1, wave, lane, epi);
	v_mfma_f32_32x32x16_bf16 v[0:15], v[194:197], v[202:205], v[0:15]
	s_waitcnt vmcnt(7)
	s_nop 10
	v_mul_f32_e32 v189, v8, v207
	v_mul_f32_e32 v194, v0, v207
	v_fmac_f32_e32 v189, v0, v206
	v_fma_f32 v0, v8, v206, -v194
	v_mul_f32_e32 v0, 0x3e000000, v0
	v_mul_f32_e32 v8, 0x3e000000, v189
	v_cvt_pk_bf16_f32 v0, v8, v0
	global_store_short v[192:193], v0, off offset:1536
	global_store_short_d16_hi v[192:193], v0, off offset:3584
	v_add_co_u32_e32 v194, vcc, s45, v208
	s_nop 1
	v_addc_co_u32_e32 v195, vcc, 0, v209, vcc
	s_waitcnt vmcnt(8)
	v_mul_f32_e32 v0, v9, v225
	v_mul_f32_e32 v8, v1, v225
	v_fmac_f32_e32 v0, v1, v224
	v_fma_f32 v1, v9, v224, -v8
	v_mul_f32_e32 v0, 0x3e000000, v0
	v_mul_f32_e32 v1, 0x3e000000, v1
	v_cvt_pk_bf16_f32 v0, v0, v1
	global_store_short v[194:195], v0, off offset:1536
	global_store_short_d16_hi v[194:195], v0, off offset:3584
	v_add_co_u32_e32 v190, vcc, s64, v208
	s_nop 1
	v_addc_co_u32_e32 v191, vcc, 0, v209, vcc
	s_waitcnt vmcnt(9)
	v_mul_f32_e32 v189, v10, v227
	v_mul_f32_e32 v1, v2, v227
	v_fmac_f32_e32 v189, v2, v226
	v_fma_f32 v0, v10, v226, -v1
	v_mul_f32_e32 v0, 0x3e000000, v0
	v_mul_f32_e32 v1, 0x3e000000, v189
	v_cvt_pk_bf16_f32 v0, v1, v0
	global_store_short v[190:191], v0, off offset:1536
	global_store_short_d16_hi v[190:191], v0, off offset:3584
	v_add_co_u32_e32 v190, vcc, s65, v208
	s_nop 1
	v_addc_co_u32_e32 v191, vcc, 0, v209, vcc
	s_waitcnt vmcnt(10)
	v_mul_f32_e32 v2, v11, v229
	v_mul_f32_e32 v1, v3, v229
	v_fmac_f32_e32 v2, v3, v228
	v_fma_f32 v0, v11, v228, -v1
	v_mul_f32_e32 v0, 0x3e000000, v0
	v_mul_f32_e32 v1, 0x3e000000, v2
	v_cvt_pk_bf16_f32 v0, v1, v0
	global_store_short v[190:191], v0, off offset:1536
	global_store_short_d16_hi v[190:191], v0, off offset:3584
	v_lshl_add_u64 v[2:3], s[26:27], 0, v[44:45]
	v_add_co_u32_e32 v10, vcc, s44, v2
	s_nop 1
	v_addc_co_u32_e32 v11, vcc, 0, v3, vcc
	v_lshl_add_u64 v[44:45], v[44:45], 0, s[56:57]
	s_waitcnt vmcnt(11)
	v_mul_f32_e32 v189, v12, v231
	v_mul_f32_e32 v1, v4, v231
	v_fmac_f32_e32 v189, v4, v230
	v_fma_f32 v0, v12, v230, -v1
	v_mul_f32_e32 v0, 0x3e000000, v0
	v_mul_f32_e32 v1, 0x3e000000, v189
	v_cvt_pk_bf16_f32 v0, v1, v0
	global_store_short v[10:11], v0, off offset:1536
	global_store_short_d16_hi v[10:11], v0, off offset:3584
	v_add_co_u32_e32 v10, vcc, s45, v2
	s_nop 1
	v_addc_co_u32_e32 v11, vcc, 0, v3, vcc
	s_waitcnt vmcnt(12)
	v_mul_f32_e32 v4, v13, v233
	v_mul_f32_e32 v1, v5, v233
	v_fmac_f32_e32 v4, v5, v232
	v_fma_f32 v0, v13, v232, -v1
	v_mul_f32_e32 v0, 0x3e000000, v0
	v_mul_f32_e32 v1, 0x3e000000, v4
	v_cvt_pk_bf16_f32 v0, v1, v0
	global_store_short v[10:11], v0, off offset:1536
	global_store_short_d16_hi v[10:11], v0, off offset:3584
	v_add_co_u32_e32 v8, vcc, s64, v2
	s_nop 1
	v_addc_co_u32_e32 v9, vcc, 0, v3, vcc
	v_add_co_u32_e32 v188, vcc, 8, v188
	s_and_b64 s[18:19], exec, vcc
	v_add_co_u32_e32 v2, vcc, 0x300e5000, v2
	s_add_i32 s63, s63, s62
	s_nop 0
	v_addc_co_u32_e32 v3, vcc, 0, v3, vcc
	s_mov_b64 vcc, s[18:19]
	s_waitcnt vmcnt(13)
	v_mul_f32_e32 v10, v14, v235
	v_mul_f32_e32 v1, v6, v235
	v_fmac_f32_e32 v10, v6, v234
	v_fma_f32 v0, v14, v234, -v1
	v_mul_f32_e32 v0, 0x3e000000, v0
	v_mul_f32_e32 v1, 0x3e000000, v10
	v_cvt_pk_bf16_f32 v0, v1, v0
	global_store_short v[8:9], v0, off offset:1536
	global_store_short_d16_hi v[8:9], v0, off offset:3584
	s_waitcnt vmcnt(14)
	v_mul_f32_e32 v4, v15, v237
	v_mul_f32_e32 v1, v7, v237
	v_fmac_f32_e32 v4, v7, v236
	v_fma_f32 v0, v15, v236, -v1
	v_mul_f32_e32 v0, 0x3e000000, v0
	v_mul_f32_e32 v1, 0x3e000000, v4
	v_cvt_pk_bf16_f32 v0, v1, v0
	global_store_short v[2:3], v0, off offset:1536
	global_store_short_d16_hi v[2:3], v0, off offset:3584
	s_cbranch_vccnz .LBB0_1203

; #define LAS __attribute__((address_space(3)))
; #define MFMA32(a, b, c) __builtin_amdgcn_mfma_f32_32x32x16_bf16((a), (b), (c), 0, 0, 0)
; __device__ __forceinline__ unsigned pk2(float lo, float hi) { return cvt_pk_bf16(lo, hi); }
; #define lane (pg8::pg8_lane_id())
; template <int MR, int KK, class Epi>
; __device__ __forceinline__ void dft_tiles(lds8* lds, const bf16_t* A, int wave, int lane, const Epi& epi) {
;     ...
;     for (int t = wave; t < (MR / 32) * 4; t += 8) { const int rb = t >> 2, nb = t & 3; f32x16 acc;
; #pragma unroll
;         for (int r = 0; r < 16; ++r) acc[r] = 0.f;
;         const int n = 32 * nb + l31, sw = (n & 15) ^ ((n >> 4) & 7);
;         const bf16_t* ap = A + (size_t)(32 * rb + l31) * KK + 8 * hh; const lds8* bp = lds + n * BS;
; #pragma unroll
;         for (int ks = 0; ks < KK / 16; ++ks) { const bf16x8 av = *(const bf16x8*)(ap + 16 * ks); const bf16x8 bv = *(const LAS bf16x8*)(bp + (((2 * ks + hh) ^ sw) << 4)); acc = MFMA32(av, bv, acc); }
;         epi(rb, nb, acc); }
; template <int S1>
; __device__ __forceinline__ void fourier_a_unit(lds8* lds, const bf16_t* H, bf16_t* TB, const bf16_t* G1, const float* tw, int seqb, int s2, int g, int tid, int lane, int wave) {
;     ...
;     auto epi = [&](int rb, int nb, const f32x16& acc) {
; #pragma unroll
;         for (int r = 0; r < 8; ++r) { const int k1 = 16 * rb + (r & 3) + 8 * (r >> 2) + 4 * hh; const f32x2v cs = *(const f32x2v*)(tw + 2 * (s2 * k1));
;             const float c = cs.x, s = cs.y; const float tr = acc[r], ti = acc[r + 8];
;             bf16_t* o = TB + ((size_t)seqb + (size_t)k1 * S1 + s2) * DM + g * 128 + 32 * nb + l31;
;             const unsigned w = pk2((tr * c + ti * s) * sc, (ti * c - tr * s) * sc); o[0] = (bf16_t)(w & 0xffffu); o[1024] = (bf16_t)(w >> 16); } };
;     dft_tiles<2 * S1, 2 * S1>(lds, G1, wave, lane, epi);
.LBB0_1224:
	v_lshl_add_u64 v[0:1], s[26:27], 0, v[48:49]
	v_add_u32_e32 v2, s18, v187
	v_add_co_u32_e32 v212, vcc, 0xbc40000, v0
	v_ashrrev_i32_e32 v3, 31, v2
	s_nop 0
	v_addc_co_u32_e32 v213, vcc, 0, v1, vcc
	v_lshl_add_u64 v[214:215], v[2:3], 2, s[50:51]
	global_load_dwordx4 v[0:3], v[212:213], off
	global_load_dwordx4 v[188:191], v[212:213], off offset:32
	global_load_dwordx4 v[192:195], v[212:213], off offset:64
	global_load_dwordx4 v[196:199], v[212:213], off offset:96
	s_and_b32 s8, s62, 0x60
	v_or_b32_e32 v4, s8, v55
	v_lshrrev_b32_e32 v5, 4, v4
	v_xor_b32_e32 v217, v5, v56
	v_lshl_add_u32 v216, v4, 9, 0
	v_xor_b32_e32 v4, v217, v54
	v_xor_b32_e32 v5, v217, v57
	v_lshl_add_u32 v4, v4, 4, v216
	v_lshl_add_u32 v8, v5, 4, v216
	ds_read_b128 v[4:7], v4
	ds_read_b128 v[200:203], v8
	global_load_dwordx4 v[204:207], v[212:213], off offset:128
	global_load_dwordx4 v[208:211], v[212:213], off offset:160
	v_xor_b32_e32 v218, v217, v58
	v_xor_b32_e32 v219, v217, v59
	s_addk_i32 s62, 0x100
	s_add_i32 s30, s30, 8
	v_lshl_add_u64 v[48:49], v[48:49], 0, s[58:59]
	s_waitcnt vmcnt(5) lgkmcnt(1)
	v_mfma_f32_32x32x16_bf16 v[0:15], v[0:3], v[4:7], 0
	s_waitcnt vmcnt(4) lgkmcnt(0)
	v_mfma_f32_32x32x16_bf16 v[0:15], v[188:191], v[200:203], v[0:15]
	v_lshl_add_u32 v188, v218, 4, v216
	v_lshl_add_u32 v200, v219, 4, v216
	ds_read_b128 v[188:191], v188
	ds_read_b128 v[200:203], v200
	v_xor_b32_e32 v218, v217, v60
	v_xor_b32_e32 v219, v217, v61
	s_waitcnt vmcnt(3) lgkmcnt(1)
	v_mfma_f32_32x32x16_bf16 v[0:15], v[192:195], v[188:191], v[0:15]
	global_load_dwordx4 v[188:191], v[212:213], off offset:192
	global_load_dwordx4 v[192:195], v[212:213], off offset:224
	s_waitcnt vmcnt(4) lgkmcnt(0)
	v_mfma_f32_32x32x16_bf16 v[0:15], v[196:199], v[200:203], v[0:15]
	v_lshl_add_u32 v196, v218, 4, v216
	v_lshl_add_u32 v200, v219, 4, v216
	ds_read_b128 v[196:199], v196
	ds_read_b128 v[200:203], v200
	v_xor_b32_e32 v218, v217, v62
	v_xor_b32_e32 v219, v217, v63
	s_waitcnt vmcnt(3) lgkmcnt(1)
	v_mfma_f32_32x32x16_bf16 v[0:15], v[204:207], v[196:199], v[0:15]
	global_load_dwordx4 v[196:199], v[212:213], off offset:256
	global_load_dwordx4 v[204:207], v[212:213], off offset:288
	s_waitcnt vmcnt(4) lgkmcnt(0)
	v_mfma_f32_32x32x16_bf16 v[0:15], v[208:211], v[200:203], v[0:15]
	v_lshl_add_u32 v200, v218, 4, v216
	v_lshl_add_u32 v208, v219, 4, v216
	ds_read_b128 v[200:203], v200
	ds_read_b128 v[208:211], v208
	v_xor_b32_e32 v218, v217, v65
	v_xor_b32_e32 v219, v217, v66
	s_waitcnt vmcnt(3) lgkmcnt(1)
	v_mfma_f32_32x32x16_bf16 v[0:15], v[188:191], v[200:203], v[0:15]
	global_load_dwordx4 v[188:191], v[212:213], off offset:320
	global_load_dwordx4 v[200:203], v[212:213], off offset:352
	s_waitcnt vmcnt(4) lgkmcnt(0)
	v_mfma_f32_32x32x16_bf16 v[0:15], v[192:195], v[208:211], v[0:15]
	v_lshl_add_u32 v192, v218, 4, v216
	v_lshl_add_u32 v208, v219, 4, v216
	ds_read_b128 v[192:195], v192
	ds_read_b128 v[208:211], v208
	v_xor_b32_e32 v218, v217, v67
	v_xor_b32_e32 v219, v217, v68
	s_waitcnt vmcnt(3) lgkmcnt(1)
	v_mfma_f32_32x32x16_bf16 v[0:15], v[196:199], v[192:195], v[0:15]
	global_load_dwordx4 v[192:195], v[212:213], off offset:384
	global_load_dwordx4 v[196:199], v[212:213], off offset:416
	s_waitcnt vmcnt(4) lgkmcnt(0)
	v_mfma_f32_32x32x16_bf16 v[0:15], v[204:207], v[208:211], v[0:15]
	v_lshl_add_u32 v204, v218, 4, v216
	v_lshl_add_u32 v208, v219, 4, v216
	ds_read_b128 v[204:207], v204
	ds_read_b128 v[208:211], v208
	s_waitcnt vmcnt(3) lgkmcnt(1)
	v_mfma_f32_32x32x16_bf16 v[0:15], v[188:191], v[204:207], v[0:15]
	global_load_dwordx4 v[188:191], v[212:213], off offset:448
	global_load_dwordx4 v[204:207], v[212:213], off offset:480
	v_xor_b32_e32 v212, v217, v69
	v_xor_b32_e32 v213, v217, v70
	s_waitcnt vmcnt(4) lgkmcnt(0)
	v_mfma_f32_32x32x16_bf16 v[0:15], v[200:203], v[208:211], v[0:15]
	v_lshl_add_u32 v200, v212, 4, v216
	v_lshl_add_u32 v208, v213, 4, v216
	ds_read_b128 v[200:203], v200
	ds_read_b128 v[208:211], v208
	s_waitcnt vmcnt(3) lgkmcnt(1)
	v_mfma_f32_32x32x16_bf16 v[0:15], v[192:195], v[200:203], v[0:15]
	global_load_dwordx2 v[200:201], v[214:215], off
	v_add_u32_e32 v238, s18, v186
	v_ashrrev_i32_e32 v239, 31, v238
	v_lshl_add_u64 v[238:239], v[238:239], 2, s[50:51]
	global_load_dwordx2 v[238:239], v[238:239], off
	v_add_u32_e32 v240, s18, v185
	v_ashrrev_i32_e32 v241, 31, v240
	v_lshl_add_u64 v[240:241], v[240:241], 2, s[50:51]
	global_load_dwordx2 v[240:241], v[240:241], off
	v_add_u32_e32 v242, s18, v184
	v_ashrrev_i32_e32 v243, 31, v242
	v_lshl_add_u64 v[242:243], v[242:243], 2, s[50:51]
	global_load_dwordx2 v[242:243], v[242:243], off
	v_add_u32_e32 v244, s18, v183
	v_ashrrev_i32_e32 v245, 31, v244
	v_lshl_add_u64 v[244:245], v[244:245], 2, s[50:51]
	global_load_dwordx2 v[244:245], v[244:245], off
	v_add_u32_e32 v246, s18, v182
	v_ashrrev_i32_e32 v247, 31, v246
	v_lshl_add_u64 v[246:247], v[246:247], 2, s[50:51]
	global_load_dwordx2 v[246:247], v[246:247], off
	v_add_u32_e32 v248, s18, v181
	v_ashrrev_i32_e32 v249, 31, v248
	v_lshl_add_u64 v[248:249], v[248:249], 2, s[50:51]
	global_load_dwordx2 v[248:249], v[248:249], off
	v_add_u32_e32 v250, s18, v180
	v_ashrrev_i32_e32 v251, 31, v250
	v_lshl_add_u64 v[250:251], v[250:251], 2, s[50:51]
	global_load_dwordx2 v[250:251], v[250:251], off
	v_xor_b32_e32 v192, v217, v71
	v_xor_b32_e32 v193, v217, v72
	v_lshl_add_u32 v192, v192, 4, v216
	v_lshl_add_u64 v[202:203], s[26:27], 0, v[46:47]
	v_lshl_add_u64 v[46:47], v[46:47], 0, s[60:61]
	s_waitcnt vmcnt(10) lgkmcnt(0)
; __device__ __forceinline__ unsigned pk2(float lo, float hi) { return cvt_pk_bf16(lo, hi); }
; #define lane (pg8::pg8_lane_id())
; template <int S1>
; __device__ __forceinline__ void fourier_a_unit(lds8* lds, const bf16_t* H, bf16_t* TB, const bf16_t* G1, const float* tw, int seqb, int s2, int g, int tid, int lane, int wave) {
;     ...
;     auto epi = [&](int rb, int nb, const f32x16& acc) {
; #pragma unroll
;         for (int r = 0; r < 8; ++r) { const int k1 = 16 * rb + (r & 3) + 8 * (r >> 2) + 4 * hh; const f32x2v cs = *(const f32x2v*)(tw + 2 * (s2 * k1));
;             const float c = cs.x, s = cs.y; const float tr = acc[r], ti = acc[r + 8];
;             bf16_t* o = TB + ((size_t)seqb + (size_t)k1 * S1 + s2) * DM + g * 128 + 32 * nb + l31;
;             const unsigned w = pk2((tr * c + ti * s) * sc, (ti * c - tr * s) * sc); o[0] = (bf16_t)(w & 0xffffu); o[1024] = (bf16_t)(w >> 16); } };
;     dft_tiles<2 * S1, 2 * S1>(lds, G1, wave, lane, epi);
	v_mfma_f32_32x32x16_bf16 v[0:15], v[196:199], v[208:211], v[0:15]
	v_lshl_add_u32 v196, v193, 4, v216
	ds_read_b128 v[192:195], v192
	ds_read_b128 v[196:199], v196
	s_waitcnt vmcnt(9) lgkmcnt(1)
	v_mfma_f32_32x32x16_bf16 v[0:15], v[188:191], v[192:195], v[0:15]
	v_add_co_u32_e32 v190, vcc, s44, v202
	s_nop 1
	v_addc_co_u32_e32 v191, vcc, 0, v203, vcc
	s_waitcnt vmcnt(8) lgkmcnt(0)
	v_mfma_f32_32x32x16_bf16 v[0:15], v[204:207], v[196:199], v[0:15]
	s_waitcnt vmcnt(7)
	s_nop 10
	v_mul_f32_e32 v192, v8, v201
	v_mul_f32_e32 v193, v0, v201
	v_fmac_f32_e32 v192, v0, v200
	v_fma_f32 v0, v8, v200, -v193
	v_mul_f32_e32 v0, 0x3db504f3, v0
	v_mul_f32_e32 v8, 0x3db504f3, v192
	v_cvt_pk_bf16_f32 v0, v8, v0
	global_store_short v[190:191], v0, off offset:1536
	global_store_short_d16_hi v[190:191], v0, off offset:3584
	v_add_co_u32_e32 v192, vcc, s64, v202
	s_nop 1
	v_addc_co_u32_e32 v193, vcc, 0, v203, vcc
	s_waitcnt vmcnt(8)
	v_mul_f32_e32 v0, v9, v239
	v_mul_f32_e32 v8, v1, v239
	v_fmac_f32_e32 v0, v1, v238
	v_fma_f32 v1, v9, v238, -v8
	v_mul_f32_e32 v0, 0x3db504f3, v0
	v_mul_f32_e32 v1, 0x3db504f3, v1
	v_cvt_pk_bf16_f32 v0, v0, v1
	global_store_short v[192:193], v0, off offset:1536
	global_store_short_d16_hi v[192:193], v0, off offset:3584
	v_add_co_u32_e32 v188, vcc, s66, v202
	s_nop 1
	v_addc_co_u32_e32 v189, vcc, 0, v203, vcc
	s_waitcnt vmcnt(9)
	v_mul_f32_e32 v190, v10, v241
	v_mul_f32_e32 v1, v2, v241
	v_fmac_f32_e32 v190, v2, v240
	v_fma_f32 v0, v10, v240, -v1
	v_mul_f32_e32 v0, 0x3db504f3, v0
	v_mul_f32_e32 v1, 0x3db504f3, v190
	v_cvt_pk_bf16_f32 v0, v1, v0
	global_store_short v[188:189], v0, off offset:1536
	global_store_short_d16_hi v[188:189], v0, off offset:3584
	v_add_co_u32_e32 v188, vcc, s67, v202
	s_nop 1
	v_addc_co_u32_e32 v189, vcc, 0, v203, vcc
	s_waitcnt vmcnt(10)
	v_mul_f32_e32 v2, v11, v243
	v_mul_f32_e32 v1, v3, v243
	v_fmac_f32_e32 v2, v3, v242
	v_fma_f32 v0, v11, v242, -v1
	v_mul_f32_e32 v0, 0x3db504f3, v0
	v_mul_f32_e32 v1, 0x3db504f3, v2
	v_cvt_pk_bf16_f32 v0, v1, v0
	global_store_short v[188:189], v0, off offset:1536
	global_store_short_d16_hi v[188:189], v0, off offset:3584
	v_lshl_add_u64 v[2:3], s[26:27], 0, v[44:45]
	v_add_co_u32_e32 v10, vcc, s44, v2
	s_nop 1
	v_addc_co_u32_e32 v11, vcc, 0, v3, vcc
	v_lshl_add_u64 v[44:45], v[44:45], 0, s[60:61]
	s_waitcnt vmcnt(11)
	v_mul_f32_e32 v188, v12, v245
	v_mul_f32_e32 v1, v4, v245
	v_fmac_f32_e32 v188, v4, v244
	v_fma_f32 v0, v12, v244, -v1
	v_mul_f32_e32 v0, 0x3db504f3, v0
	v_mul_f32_e32 v1, 0x3db504f3, v188
	v_cvt_pk_bf16_f32 v0, v1, v0
	global_store_short v[10:11], v0, off offset:1536
	global_store_short_d16_hi v[10:11], v0, off offset:3584
	v_add_co_u32_e32 v10, vcc, s64, v2
	s_nop 1
	v_addc_co_u32_e32 v11, vcc, 0, v3, vcc
	s_waitcnt vmcnt(12)
	v_mul_f32_e32 v4, v13, v247
	v_mul_f32_e32 v1, v5, v247
	v_fmac_f32_e32 v4, v5, v246
	v_fma_f32 v0, v13, v246, -v1
	v_mul_f32_e32 v0, 0x3db504f3, v0
	v_mul_f32_e32 v1, 0x3db504f3, v4
	v_cvt_pk_bf16_f32 v0, v1, v0
	global_store_short v[10:11], v0, off offset:1536
	global_store_short_d16_hi v[10:11], v0, off offset:3584
	v_add_co_u32_e32 v8, vcc, s66, v2
	s_nop 1
	v_addc_co_u32_e32 v9, vcc, 0, v3, vcc
	s_add_i32 s18, s18, s19
	v_add_co_u32_e32 v2, vcc, 0x301a5000, v2
	s_cmp_gt_u32 s30, 23
	s_nop 0
	v_addc_co_u32_e32 v3, vcc, 0, v3, vcc
	s_waitcnt vmcnt(13)
	v_mul_f32_e32 v10, v14, v249
	v_mul_f32_e32 v1, v6, v249
	v_fmac_f32_e32 v10, v6, v248
	v_fma_f32 v0, v14, v248, -v1
	v_mul_f32_e32 v0, 0x3db504f3, v0
	v_mul_f32_e32 v1, 0x3db504f3, v10
	v_cvt_pk_bf16_f32 v0, v1, v0
	global_store_short v[8:9], v0, off offset:1536
	global_store_short_d16_hi v[8:9], v0, off offset:3584
	s_waitcnt vmcnt(14)
	v_mul_f32_e32 v4, v15, v251
	v_mul_f32_e32 v1, v7, v251
	v_fmac_f32_e32 v4, v7, v250
	v_fma_f32 v0, v15, v250, -v1
	v_mul_f32_e32 v0, 0x3db504f3, v0
	v_mul_f32_e32 v1, 0x3db504f3, v4
	v_cvt_pk_bf16_f32 v0, v1, v0
	global_store_short v[2:3], v0, off offset:1536
	global_store_short_d16_hi v[2:3], v0, off offset:3584
	s_cbranch_scc0 .LBB0_1224
	s_branch .LBB0_1191
